# hyena filter-even streaming loop: 24 loads of the 8 trips issued up front, bodies behind counted vmcnt
# speedup vs baseline: 1.0250x; 1.0057x over previous
.LBB0_1009:
	s_or_b64 exec, exec, s[0:1]
	s_waitcnt lgkmcnt(0)
	s_barrier
	ds_read_b128 v[60:63], v138
	ds_read_b128 v[64:67], v138 offset:16
	ds_read_b128 v[52:55], v138 offset:16384
	ds_read_b128 v[56:59], v138 offset:16400
	s_waitcnt vmcnt(0)
	ds_read_b128 v[44:47], v138 offset:32768
	ds_read_b128 v[48:51], v138 offset:32784
	ds_read_b128 v[36:39], v138 offset:49152
	ds_read_b128 v[40:43], v138 offset:49168
	ds_read_b128 v[28:31], v139
	ds_read_b128 v[32:35], v140
	ds_read_b128 v[20:23], v141
	ds_read_b128 v[24:27], v142
	ds_read_b128 v[12:15], v143
	ds_read_b128 v[16:19], v144
	ds_read_b128 v[4:7], v145
	ds_read_b128 v[8:11], v146
	s_add_i32 s4, s9, s50
	s_add_i32 s0, s4, 0x400
	s_ashr_i32 s5, s4, 31
	s_ashr_i32 s1, s0, 31
	v_readlane_b32 s64, v251, 2
	s_lshl_b64 s[56:57], s[4:5], 16
	s_lshl_b64 s[58:59], s[0:1], 16
	v_readlane_b32 s76, v251, 14
	v_readlane_b32 s77, v251, 15
	s_add_u32 s54, s76, s58
	v_mov_b32_e32 v0, v179
	s_addc_u32 s55, s77, s59
	v_mov_b32_e32 v79, 0
	v_cmp_gt_i32_e32 vcc, s37, v0
	v_readlane_b32 s65, v251, 3
	v_readlane_b32 s66, v251, 4
	v_readlane_b32 s67, v251, 5
	v_readlane_b32 s68, v251, 6
	v_readlane_b32 s69, v251, 7
	v_readlane_b32 s70, v251, 8
	v_readlane_b32 s71, v251, 9
	v_readlane_b32 s72, v251, 10
	v_readlane_b32 s73, v251, 11
	v_readlane_b32 s74, v251, 12
	v_readlane_b32 s75, v251, 13
	v_readlane_b32 s78, v251, 16
	v_readlane_b32 s79, v251, 17
	s_and_saveexec_b64 s[0:1], vcc
	s_cbranch_execz .LBB0_1015
	v_lshlrev_b32_e32 v78, 2, v0
	v_ashrrev_i32_e32 v79, 31, v78
	v_lshlrev_b64 v[2:3], 2, v[78:79]
	v_lshl_add_u32 v75, v0, 5, 32
	v_mov_b32_e32 v0, s59
	v_sub_co_u32_e32 v68, vcc, s58, v2
	v_readlane_b32 s2, v253, 39
	s_nop 0
	v_subb_co_u32_e32 v69, vcc, v0, v3, vcc
	v_readlane_b32 s3, v253, 40
	v_sub_u32_e32 v76, 0x4000, v78
	v_mov_b32_e32 v79, 0
	v_lshl_add_u64 v[80:81], s[2:3], 0, v[68:69]
	v_readlane_b32 s2, v253, 41
	s_add_u32 s2, s2, s56
	v_readlane_b32 s3, v253, 42
	s_addc_u32 s3, s3, s57
	s_nop 0
	v_lshl_add_u64 v[82:83], s[2:3], 0, v[2:3]
	v_mov_b32_e32 v77, v1
	global_load_dwordx4 v[88:91], v[82:83], off offset:-8
	global_load_dwordx3 v[92:94], v[80:81], off offset:-8
	v_cmp_lt_i32_e32 vcc, 0, v78
	v_mov_b32_e32 v95, 0
	s_and_saveexec_b64 s[24:25], vcc
	v_lshl_add_u64 v[2:3], v[76:77], 2, s[54:55]
	global_load_dword v95, v[2:3], off
	s_or_b64 exec, exec, s[24:25]
	s_mov_b64 s[2:3], 0x2000
	s_mov_b32 s24, 0xffffe000
	s_mov_b32 s25, -1
	v_lshl_add_u64 v[82:83], v[82:83], 0, s[2:3]
	v_lshl_add_u64 v[80:81], v[80:81], 0, s[24:25]
	v_add_u32_e32 v76, 0xfffff800, v76
	global_load_dwordx4 v[96:99], v[82:83], off offset:-8
	global_load_dwordx3 v[100:102], v[80:81], off offset:-8
	v_lshl_add_u64 v[2:3], v[76:77], 2, s[54:55]
	global_load_dword v103, v[2:3], off
	v_lshl_add_u64 v[82:83], v[82:83], 0, s[2:3]
	v_lshl_add_u64 v[80:81], v[80:81], 0, s[24:25]
	v_add_u32_e32 v76, 0xfffff800, v76
	global_load_dwordx4 v[104:107], v[82:83], off offset:-8
	global_load_dwordx3 v[108:110], v[80:81], off offset:-8
	v_lshl_add_u64 v[2:3], v[76:77], 2, s[54:55]
	global_load_dword v111, v[2:3], off
	v_lshl_add_u64 v[82:83], v[82:83], 0, s[2:3]
	v_lshl_add_u64 v[80:81], v[80:81], 0, s[24:25]
	v_add_u32_e32 v76, 0xfffff800, v76
	global_load_dwordx4 v[112:115], v[82:83], off offset:-8
	global_load_dwordx3 v[116:118], v[80:81], off offset:-8
	v_lshl_add_u64 v[2:3], v[76:77], 2, s[54:55]
	global_load_dword v119, v[2:3], off
	v_lshl_add_u64 v[82:83], v[82:83], 0, s[2:3]
	v_lshl_add_u64 v[80:81], v[80:81], 0, s[24:25]
	v_add_u32_e32 v76, 0xfffff800, v76
	global_load_dwordx4 v[120:123], v[82:83], off offset:-8
	global_load_dwordx3 v[124:126], v[80:81], off offset:-8
	v_lshl_add_u64 v[2:3], v[76:77], 2, s[54:55]
	global_load_dword v127, v[2:3], off
	v_lshl_add_u64 v[82:83], v[82:83], 0, s[2:3]
	v_lshl_add_u64 v[80:81], v[80:81], 0, s[24:25]
	v_add_u32_e32 v76, 0xfffff800, v76
	global_load_dwordx4 v[128:131], v[82:83], off offset:-8
	global_load_dwordx3 v[132:134], v[80:81], off offset:-8
	v_lshl_add_u64 v[2:3], v[76:77], 2, s[54:55]
	global_load_dword v135, v[2:3], off
	v_lshl_add_u64 v[82:83], v[82:83], 0, s[2:3]
	v_lshl_add_u64 v[80:81], v[80:81], 0, s[24:25]
	v_add_u32_e32 v76, 0xfffff800, v76
	global_load_dwordx4 v[150:153], v[82:83], off offset:-8
	global_load_dwordx3 v[154:156], v[80:81], off offset:-8
	v_lshl_add_u64 v[2:3], v[76:77], 2, s[54:55]
	global_load_dword v157, v[2:3], off
	v_lshl_add_u64 v[82:83], v[82:83], 0, s[2:3]
	v_lshl_add_u64 v[80:81], v[80:81], 0, s[24:25]
	v_add_u32_e32 v76, 0xfffff800, v76
	global_load_dwordx4 v[158:161], v[82:83], off offset:-8
	global_load_dwordx3 v[162:164], v[80:81], off offset:-8
	v_lshl_add_u64 v[2:3], v[76:77], 2, s[54:55]
	global_load_dword v165, v[2:3], off
	s_waitcnt vmcnt(21)
	v_and_b32_e32 v3, 0x7fffffff, v89
	v_and_b32_e32 v2, 0x7fffffff, v88
	v_and_b32_e32 v84, 0x7fffffff, v95
	v_and_b32_e32 v85, 0x7fffffff, v94
	v_pk_add_f32 v[2:3], v[2:3], v[84:85]
	v_and_b32_e32 v85, 0x7fffffff, v90
	v_add_f32_e32 v2, v79, v2
	v_and_b32_e32 v84, 0x7fffffff, v91
	v_and_b32_e32 v87, 0x7fffffff, v93
	v_and_b32_e32 v86, 0x7fffffff, v92
	v_add_f32_e32 v0, v88, v95
	v_add_f32_e32 v3, v3, v2
	v_pk_add_f32 v[84:85], v[84:85], v[86:87]
	v_add_f32_e32 v2, v89, v94
	v_add_f32_e32 v68, v90, v93
	v_add_f32_e32 v3, v85, v3
	v_add_f32_e32 v79, v84, v3
	v_add_f32_e32 v70, v91, v92
	v_mov_b32_e32 v3, v1
	v_mov_b32_e32 v69, v1
	v_mov_b32_e32 v71, v1
	ds_write_b128 v75, v[0:3]
	ds_write_b128 v75, v[68:71] offset:16
	v_add_u32_e32 v75, 0x4000, v75
	s_waitcnt vmcnt(18)
	v_and_b32_e32 v3, 0x7fffffff, v97
	v_and_b32_e32 v2, 0x7fffffff, v96
	v_and_b32_e32 v84, 0x7fffffff, v103
	v_and_b32_e32 v85, 0x7fffffff, v102
	v_pk_add_f32 v[2:3], v[2:3], v[84:85]
	v_and_b32_e32 v85, 0x7fffffff, v98
	v_add_f32_e32 v2, v79, v2
	v_and_b32_e32 v84, 0x7fffffff, v99
	v_and_b32_e32 v87, 0x7fffffff, v101
	v_and_b32_e32 v86, 0x7fffffff, v100
	v_add_f32_e32 v0, v96, v103
	v_add_f32_e32 v3, v3, v2
	v_pk_add_f32 v[84:85], v[84:85], v[86:87]
	v_add_f32_e32 v2, v97, v102
	v_add_f32_e32 v68, v98, v101
	v_add_f32_e32 v3, v85, v3
	v_add_f32_e32 v79, v84, v3
	v_add_f32_e32 v70, v99, v100
	v_mov_b32_e32 v3, v1
	v_mov_b32_e32 v69, v1
	v_mov_b32_e32 v71, v1
	ds_write_b128 v75, v[0:3]
	ds_write_b128 v75, v[68:71] offset:16
	v_add_u32_e32 v75, 0x4000, v75
	s_waitcnt vmcnt(15)
	v_and_b32_e32 v3, 0x7fffffff, v105
	v_and_b32_e32 v2, 0x7fffffff, v104
	v_and_b32_e32 v84, 0x7fffffff, v111
	v_and_b32_e32 v85, 0x7fffffff, v110
	v_pk_add_f32 v[2:3], v[2:3], v[84:85]
	v_and_b32_e32 v85, 0x7fffffff, v106
	v_add_f32_e32 v2, v79, v2
	v_and_b32_e32 v84, 0x7fffffff, v107
	v_and_b32_e32 v87, 0x7fffffff, v109
	v_and_b32_e32 v86, 0x7fffffff, v108
	v_add_f32_e32 v0, v104, v111
	v_add_f32_e32 v3, v3, v2
	v_pk_add_f32 v[84:85], v[84:85], v[86:87]
	v_add_f32_e32 v2, v105, v110
	v_add_f32_e32 v68, v106, v109
	v_add_f32_e32 v3, v85, v3
	v_add_f32_e32 v79, v84, v3
	v_add_f32_e32 v70, v107, v108
	v_mov_b32_e32 v3, v1
	v_mov_b32_e32 v69, v1
	v_mov_b32_e32 v71, v1
	ds_write_b128 v75, v[0:3]
	ds_write_b128 v75, v[68:71] offset:16
	v_add_u32_e32 v75, 0x4000, v75
	s_waitcnt vmcnt(12)
	v_and_b32_e32 v3, 0x7fffffff, v113
	v_and_b32_e32 v2, 0x7fffffff, v112
	v_and_b32_e32 v84, 0x7fffffff, v119
	v_and_b32_e32 v85, 0x7fffffff, v118
	v_pk_add_f32 v[2:3], v[2:3], v[84:85]
	v_and_b32_e32 v85, 0x7fffffff, v114
	v_add_f32_e32 v2, v79, v2
	v_and_b32_e32 v84, 0x7fffffff, v115
	v_and_b32_e32 v87, 0x7fffffff, v117
	v_and_b32_e32 v86, 0x7fffffff, v116
	v_add_f32_e32 v0, v112, v119
	v_add_f32_e32 v3, v3, v2
	v_pk_add_f32 v[84:85], v[84:85], v[86:87]
	v_add_f32_e32 v2, v113, v118
	v_add_f32_e32 v68, v114, v117
	v_add_f32_e32 v3, v85, v3
	v_add_f32_e32 v79, v84, v3
	v_add_f32_e32 v70, v115, v116
	v_mov_b32_e32 v3, v1
	v_mov_b32_e32 v69, v1
	v_mov_b32_e32 v71, v1
	ds_write_b128 v75, v[0:3]
	ds_write_b128 v75, v[68:71] offset:16
	v_add_u32_e32 v75, 0x4000, v75
	s_waitcnt vmcnt(9)
	v_and_b32_e32 v3, 0x7fffffff, v121
	v_and_b32_e32 v2, 0x7fffffff, v120
	v_and_b32_e32 v84, 0x7fffffff, v127
	v_and_b32_e32 v85, 0x7fffffff, v126
	v_pk_add_f32 v[2:3], v[2:3], v[84:85]
	v_and_b32_e32 v85, 0x7fffffff, v122
	v_add_f32_e32 v2, v79, v2
	v_and_b32_e32 v84, 0x7fffffff, v123
	v_and_b32_e32 v87, 0x7fffffff, v125
	v_and_b32_e32 v86, 0x7fffffff, v124
	v_add_f32_e32 v0, v120, v127
	v_add_f32_e32 v3, v3, v2
	v_pk_add_f32 v[84:85], v[84:85], v[86:87]
	v_add_f32_e32 v2, v121, v126
	v_add_f32_e32 v68, v122, v125
	v_add_f32_e32 v3, v85, v3
	v_add_f32_e32 v79, v84, v3
	v_add_f32_e32 v70, v123, v124
	v_mov_b32_e32 v3, v1
	v_mov_b32_e32 v69, v1
	v_mov_b32_e32 v71, v1
	ds_write_b128 v75, v[0:3]
	ds_write_b128 v75, v[68:71] offset:16
	v_add_u32_e32 v75, 0x4000, v75
	s_waitcnt vmcnt(6)
	v_and_b32_e32 v3, 0x7fffffff, v129
	v_and_b32_e32 v2, 0x7fffffff, v128
	v_and_b32_e32 v84, 0x7fffffff, v135
	v_and_b32_e32 v85, 0x7fffffff, v134
	v_pk_add_f32 v[2:3], v[2:3], v[84:85]
	v_and_b32_e32 v85, 0x7fffffff, v130
	v_add_f32_e32 v2, v79, v2
	v_and_b32_e32 v84, 0x7fffffff, v131
	v_and_b32_e32 v87, 0x7fffffff, v133
	v_and_b32_e32 v86, 0x7fffffff, v132
	v_add_f32_e32 v0, v128, v135
	v_add_f32_e32 v3, v3, v2
	v_pk_add_f32 v[84:85], v[84:85], v[86:87]
	v_add_f32_e32 v2, v129, v134
	v_add_f32_e32 v68, v130, v133
	v_add_f32_e32 v3, v85, v3
	v_add_f32_e32 v79, v84, v3
	v_add_f32_e32 v70, v131, v132
	v_mov_b32_e32 v3, v1
	v_mov_b32_e32 v69, v1
	v_mov_b32_e32 v71, v1
	ds_write_b128 v75, v[0:3]
	ds_write_b128 v75, v[68:71] offset:16
	v_add_u32_e32 v75, 0x4000, v75
	s_waitcnt vmcnt(3)
	v_and_b32_e32 v3, 0x7fffffff, v151
	v_and_b32_e32 v2, 0x7fffffff, v150
	v_and_b32_e32 v84, 0x7fffffff, v157
	v_and_b32_e32 v85, 0x7fffffff, v156
	v_pk_add_f32 v[2:3], v[2:3], v[84:85]
	v_and_b32_e32 v85, 0x7fffffff, v152
	v_add_f32_e32 v2, v79, v2
	v_and_b32_e32 v84, 0x7fffffff, v153
	v_and_b32_e32 v87, 0x7fffffff, v155
	v_and_b32_e32 v86, 0x7fffffff, v154
	v_add_f32_e32 v0, v150, v157
	v_add_f32_e32 v3, v3, v2
	v_pk_add_f32 v[84:85], v[84:85], v[86:87]
	v_add_f32_e32 v2, v151, v156
	v_add_f32_e32 v68, v152, v155
	v_add_f32_e32 v3, v85, v3
	v_add_f32_e32 v79, v84, v3
	v_add_f32_e32 v70, v153, v154
	v_mov_b32_e32 v3, v1
	v_mov_b32_e32 v69, v1
	v_mov_b32_e32 v71, v1
	ds_write_b128 v75, v[0:3]
	ds_write_b128 v75, v[68:71] offset:16
	v_add_u32_e32 v75, 0x4000, v75
	s_waitcnt vmcnt(0)
	v_and_b32_e32 v3, 0x7fffffff, v159
	v_and_b32_e32 v2, 0x7fffffff, v158
	v_and_b32_e32 v84, 0x7fffffff, v165
	v_and_b32_e32 v85, 0x7fffffff, v164
	v_pk_add_f32 v[2:3], v[2:3], v[84:85]
	v_and_b32_e32 v85, 0x7fffffff, v160
	v_add_f32_e32 v2, v79, v2
	v_and_b32_e32 v84, 0x7fffffff, v161
	v_and_b32_e32 v87, 0x7fffffff, v163
	v_and_b32_e32 v86, 0x7fffffff, v162
	v_add_f32_e32 v0, v158, v165
	v_add_f32_e32 v3, v3, v2
	v_pk_add_f32 v[84:85], v[84:85], v[86:87]
	v_add_f32_e32 v2, v159, v164
	v_add_f32_e32 v68, v160, v163
	v_add_f32_e32 v3, v85, v3
	v_add_f32_e32 v79, v84, v3
	v_add_f32_e32 v70, v161, v162
	v_mov_b32_e32 v3, v1
	v_mov_b32_e32 v69, v1
	v_mov_b32_e32 v71, v1
	ds_write_b128 v75, v[0:3]
	ds_write_b128 v75, v[68:71] offset:16
	v_add_u32_e32 v75, 0x4000, v75
	s_movk_i32 s9, 0x37ff
